# ret_out gate loads issued at the start of the unit tail (before the LayerNorm math) instead of right before use
# speedup vs baseline: 1.0024x; 1.0024x over previous
; __device__ __forceinline__ unsigned f2bf(float f) { return pk2(f, f) & 0xffffu; }
; __device__ __forceinline__ float red16(float v) { v += dpp_mov<0xB1>(v); v += dpp_mov<0x4E>(v); v += dpp_mov<0x141>(v); v += dpp_mov<0x140>(v); return v; }
; __device__ __forceinline__ void ret_out_phase(const bf16* Z, const bf16* SP, bf16* MIX, unsigned char* lds) {
;     ...
;             for (int ks = 0; ks < 2; ++ks) o2[dt] = __builtin_amdgcn_mfma_f32_16x16x32_bf16(qf[ks], tr_frag(Ss, 72, 32 * ks, 16 * dt, lane), o2[dt], 0, 0, 0); }
; #pragma unroll
;         for (int jj = 0; jj < 4; ++jj) { const int i = 16 * wave + q4 * 4 + jj; const float qd = __expf((float)(i + 1) * lg);
;             float v[4]; float s = 0.f;
; #pragma unroll
;             for (int dt = 0; dt < 4; ++dt) { v[dt] = o[dt][jj] + qd * o2[dt][jj]; s += v[dt]; }
;             const float mean = red16(s) * (1.f / 64.f); float q = 0.f;
; #pragma unroll
;             for (int dt = 0; dt < 4; ++dt) { v[dt] -= mean; q += v[dt] * v[dt]; }
;             const float rstd = rsqrtf(red16(q) * (1.f / 64.f) + 1e-6f);
; #pragma unroll
;             for (int dt = 0; dt < 4; ++dt) Ps[i * 136 + 16 * dt + r16] = (bf16)f2bf(v[dt] * rstd); }
; #pragma unroll
;         for (int t2 = 0; t2 < 2; ++t2) { const int cidx = lane + 64 * t2, i = 16 * wave + (cidx >> 3), c8 = (cidx & 7) * 8;
;             const u32x4 ov = *(const u32x4*)(Ps + i * 136 + c8), gv = *(const u32x4*)(Z + (rowbase + i) * EVEN_IN + 1536 + h * 64 + c8); u32x4 w;
.LBB0_587:
	s_or_b64 exec, exec, s[82:83]
	ds_read_b64_tr_b16 v[134:135], v132 offset:55392
	ds_read_b64_tr_b16 v[136:137], v132 offset:55968
	s_nop 3
	v_mov_b32_e32 v56, v50
	v_mov_b32_e32 v57, v42
	s_mov_b32 s82, 0x800000
	v_mov_b32_e32 v42, v51
	s_waitcnt lgkmcnt(0)
	v_mfma_f32_16x16x32_bf16 v[22:25], v[22:25], v[134:137], 0
	ds_read_b64_tr_b16 v[134:135], v132 offset:60000
	ds_read_b64_tr_b16 v[136:137], v132 offset:60576
	s_movk_i32 s89, 0x1e00
	s_lshl_b32 s16, s86, 1
	s_waitcnt lgkmcnt(0)
	v_mfma_f32_16x16x32_bf16 v[18:21], v[18:21], v[134:137], v[22:25]
	v_mov_b32_e32 v134, v26
	s_nop 1
	v_mul_f32_e32 v22, v89, v122
	v_mul_f32_e32 v22, 0x3fb8aa3b, v22
	v_exp_f32_e32 v22, v22
	s_nop 1
	v_mov_b32_e32 v24, v18
	v_mov_b32_e32 v25, v46
	v_mov_b32_e32 v135, v34
	v_pk_fma_f32 v[24:25], v[22:23], v[24:25], v[56:57] op_sel_hi:[0,1,1]
	v_mov_b32_e32 v56, v30
	v_mov_b32_e32 v57, v38
	v_pk_fma_f32 v[22:23], v[22:23], v[56:57], v[134:135] op_sel_hi:[0,1,1]
	v_add_f32_e32 v18, 0, v22
	v_add_f32_e32 v18, v18, v23
	v_add_f32_e32 v18, v18, v25
	v_add_f32_e32 v18, v18, v24
	v_mov_b32_e32 v46, v19
	v_mov_b32_e32 v38, v31
	v_add_f32_dpp v18, v18, v18 quad_perm:[1,0,3,2] row_mask:0xf bank_mask:0xf bound_ctrl:1
	v_mov_b32_e32 v34, v27
	v_lshl_add_u64 v[30:31], s[84:85], 0, v[84:85]
	v_add_f32_dpp v18, v18, v18 quad_perm:[2,3,0,1] row_mask:0xf bank_mask:0xf bound_ctrl:1
	v_mov_b64_e32 v[188:189], s[94:95]
	v_mov_b32_e32 v190, v88
	v_mov_b32_e32 v191, 0
	v_mad_u64_u32 v[178:179], vcc, v30, s89, v[188:189]
	v_lshl_add_u64 v[182:183], s[84:85], 0, v[86:87]
	v_mov_b32_e32 v180, v179
	v_mad_u64_u32 v[180:181], vcc, v31, s89, v[180:181]
	v_mov_b32_e32 v179, v180
	v_lshl_add_u64 v[178:179], v[178:179], 0, s[16:17]
	v_lshl_add_u64 v[178:179], v[178:179], 0, v[190:191]
	global_load_dwordx4 v[174:177], v[178:179], off offset:3072
	v_mad_u64_u32 v[178:179], vcc, v182, s89, v[188:189]
	v_mov_b32_e32 v180, v179
	v_mad_u64_u32 v[180:181], vcc, v183, s89, v[180:181]
	v_mov_b32_e32 v179, v180
	v_lshl_add_u64 v[178:179], v[178:179], 0, s[16:17]
	v_lshl_add_u64 v[178:179], v[178:179], 0, v[190:191]
	global_load_dwordx4 v[184:187], v[178:179], off offset:3072
	s_nop 1
	v_add_f32_dpp v18, v18, v18 row_half_mirror row_mask:0xf bank_mask:0xf bound_ctrl:1
	s_nop 1
	v_add_f32_dpp v18, v18, v18 row_mirror row_mask:0xf bank_mask:0xf bound_ctrl:1
	v_mul_f32_e32 v18, 0x3c800000, v18
	v_pk_add_f32 v[22:23], v[22:23], v[18:19] op_sel_hi:[1,0] neg_lo:[0,1] neg_hi:[0,1]
	v_pk_add_f32 v[24:25], v[24:25], v[18:19] op_sel_hi:[1,0] neg_lo:[0,1] neg_hi:[0,1]
	v_pk_mul_f32 v[56:57], v[22:23], v[22:23]
	v_pk_mul_f32 v[134:135], v[24:25], v[24:25]
	v_add_f32_e32 v18, v56, v57
	v_add_f32_e32 v18, v135, v18
	v_add_f32_e32 v18, v134, v18
	s_nop 1
	v_add_f32_dpp v18, v18, v18 quad_perm:[1,0,3,2] row_mask:0xf bank_mask:0xf bound_ctrl:1
	s_nop 1
	v_add_f32_dpp v18, v18, v18 quad_perm:[2,3,0,1] row_mask:0xf bank_mask:0xf bound_ctrl:1
	s_nop 1
	v_add_f32_dpp v18, v18, v18 row_half_mirror row_mask:0xf bank_mask:0xf bound_ctrl:1
	s_nop 1
	v_add_f32_dpp v18, v18, v18 row_mirror row_mask:0xf bank_mask:0xf bound_ctrl:1
	v_fmamk_f32 v18, v18, 0x3c800000, v164
	v_cmp_gt_f32_e32 vcc, s82, v18
	v_mul_f32_e32 v26, 0x4b800000, v18
	s_nop 0
	v_cndmask_b32_e32 v18, v18, v26, vcc
	v_rsq_f32_e32 v18, v18
	s_nop 0
	v_mul_f32_e32 v26, 0x45800000, v18
	v_cndmask_b32_e32 v18, v18, v26, vcc
	v_mul_f32_e32 v22, v22, v18
	v_cvt_pk_bf16_f32 v22, v22, v22
	ds_write_b16 v54, v22 offset:64512
	v_mul_f32_e32 v22, v23, v18
	v_cvt_pk_bf16_f32 v22, v22, v22
	ds_write_b16 v54, v22 offset:64544
	v_mul_f32_e32 v22, v25, v18
	v_mul_f32_e32 v18, v24, v18
	v_cvt_pk_bf16_f32 v18, v18, v18
	ds_write_b16 v54, v18 offset:64608
	v_mul_f32_e32 v18, v89, v123
	v_mul_f32_e32 v18, 0x3fb8aa3b, v18
	v_exp_f32_e32 v18, v18
	v_cvt_pk_bf16_f32 v22, v22, v22
	ds_write_b16 v54, v22 offset:64576
	v_pk_fma_f32 v[22:23], v[18:19], v[46:47], v[42:43] op_sel_hi:[0,1,1]
	v_pk_fma_f32 v[18:19], v[18:19], v[38:39], v[34:35] op_sel_hi:[0,1,1]
	v_add_f32_e32 v24, 0, v18
	v_add_f32_e32 v24, v24, v19
	v_add_f32_e32 v24, v24, v23
	v_add_f32_e32 v24, v24, v22
	s_nop 1
	v_add_f32_dpp v24, v24, v24 quad_perm:[1,0,3,2] row_mask:0xf bank_mask:0xf bound_ctrl:1
	s_nop 1
	v_add_f32_dpp v24, v24, v24 quad_perm:[2,3,0,1] row_mask:0xf bank_mask:0xf bound_ctrl:1
	s_nop 1
	v_add_f32_dpp v24, v24, v24 row_half_mirror row_mask:0xf bank_mask:0xf bound_ctrl:1
	s_nop 1
	v_add_f32_dpp v24, v24, v24 row_mirror row_mask:0xf bank_mask:0xf bound_ctrl:1
	v_mul_f32_e32 v24, 0x3c800000, v24
	v_pk_add_f32 v[18:19], v[18:19], v[24:25] op_sel_hi:[1,0] neg_lo:[0,1] neg_hi:[0,1]
	v_pk_add_f32 v[22:23], v[22:23], v[24:25] op_sel_hi:[1,0] neg_lo:[0,1] neg_hi:[0,1]
	v_pk_mul_f32 v[26:27], v[18:19], v[18:19]
	v_pk_mul_f32 v[24:25], v[22:23], v[22:23]
	v_add_f32_e32 v26, v26, v27
	v_add_f32_e32 v25, v25, v26
	v_add_f32_e32 v24, v24, v25
	v_mov_b32_e32 v26, v28
	v_mov_b32_e32 v27, v36
	v_add_f32_dpp v24, v24, v24 quad_perm:[1,0,3,2] row_mask:0xf bank_mask:0xf bound_ctrl:1
	v_mov_b32_e32 v36, v29
	v_mov_b64_e32 v[28:29], s[94:95]
	v_add_f32_dpp v24, v24, v24 quad_perm:[2,3,0,1] row_mask:0xf bank_mask:0xf bound_ctrl:1
	s_nop 1
	v_add_f32_dpp v24, v24, v24 row_half_mirror row_mask:0xf bank_mask:0xf bound_ctrl:1
	s_nop 1
	v_add_f32_dpp v24, v24, v24 row_mirror row_mask:0xf bank_mask:0xf bound_ctrl:1
	v_fmamk_f32 v24, v24, 0x3c800000, v164
	v_cmp_gt_f32_e32 vcc, s82, v24
	v_mul_f32_e32 v25, 0x4b800000, v24
	s_nop 0
	v_cndmask_b32_e32 v24, v24, v25, vcc
	v_rsq_f32_e32 v24, v24
	s_nop 0
	v_mul_f32_e32 v25, 0x45800000, v24
	v_cndmask_b32_e32 v24, v24, v25, vcc
	v_mul_f32_e32 v18, v18, v24
; __device__ __forceinline__ unsigned f2bf(float f) { return pk2(f, f) & 0xffffu; }
; __device__ __forceinline__ float red16(float v) { v += dpp_mov<0xB1>(v); v += dpp_mov<0x4E>(v); v += dpp_mov<0x141>(v); v += dpp_mov<0x140>(v); return v; }
; __device__ __forceinline__ void ret_out_phase(const bf16* Z, const bf16* SP, bf16* MIX, unsigned char* lds) {
;     ...
;         for (int jj = 0; jj < 4; ++jj) { const int i = 16 * wave + q4 * 4 + jj; const float qd = __expf((float)(i + 1) * lg);
;             float v[4]; float s = 0.f;
; #pragma unroll
;             for (int dt = 0; dt < 4; ++dt) { v[dt] = o[dt][jj] + qd * o2[dt][jj]; s += v[dt]; }
;             const float mean = red16(s) * (1.f / 64.f); float q = 0.f;
; #pragma unroll
;             for (int dt = 0; dt < 4; ++dt) { v[dt] -= mean; q += v[dt] * v[dt]; }
;             const float rstd = rsqrtf(red16(q) * (1.f / 64.f) + 1e-6f);
; #pragma unroll
;             for (int dt = 0; dt < 4; ++dt) Ps[i * 136 + 16 * dt + r16] = (bf16)f2bf(v[dt] * rstd); }
	v_cvt_pk_bf16_f32 v18, v18, v18
	ds_write_b16 v54, v18 offset:64784
	v_mul_f32_e32 v18, v19, v24
	v_cvt_pk_bf16_f32 v18, v18, v18
	ds_write_b16 v54, v18 offset:64816
	v_mul_f32_e32 v18, v23, v24
	v_cvt_pk_bf16_f32 v18, v18, v18
	ds_write_b16 v54, v18 offset:64848
	v_mul_f32_e32 v18, v22, v24
	v_cvt_pk_bf16_f32 v18, v18, v18
	ds_write_b16 v54, v18 offset:64880
	v_mul_f32_e32 v18, v89, v124
	v_mul_f32_e32 v18, 0x3fb8aa3b, v18
	v_exp_f32_e32 v18, v18
	v_mov_b32_e32 v22, v20
	v_mov_b32_e32 v23, v48
	v_mov_b32_e32 v24, v52
	v_mov_b32_e32 v25, v44
	v_pk_fma_f32 v[22:23], v[18:19], v[22:23], v[24:25] op_sel_hi:[0,1,1]
	v_mov_b32_e32 v24, v32
	v_mov_b32_e32 v25, v40
	v_pk_fma_f32 v[18:19], v[18:19], v[24:25], v[26:27] op_sel_hi:[0,1,1]
	v_add_f32_e32 v20, 0, v18
	v_add_f32_e32 v20, v20, v19
	v_add_f32_e32 v20, v20, v23
	v_add_f32_e32 v20, v20, v22
	v_mov_b32_e32 v48, v21
	v_mov_b32_e32 v44, v53
	v_add_f32_dpp v20, v20, v20 quad_perm:[1,0,3,2] row_mask:0xf bank_mask:0xf bound_ctrl:1
	v_mov_b32_e32 v40, v33
	s_nop 0
	v_add_f32_dpp v20, v20, v20 quad_perm:[2,3,0,1] row_mask:0xf bank_mask:0xf bound_ctrl:1
	s_nop 1
	v_add_f32_dpp v20, v20, v20 row_half_mirror row_mask:0xf bank_mask:0xf bound_ctrl:1
	s_nop 1
	v_add_f32_dpp v20, v20, v20 row_mirror row_mask:0xf bank_mask:0xf bound_ctrl:1
	v_mul_f32_e32 v20, 0x3c800000, v20
	v_pk_add_f32 v[18:19], v[18:19], v[20:21] op_sel_hi:[1,0] neg_lo:[0,1] neg_hi:[0,1]
	v_pk_add_f32 v[22:23], v[22:23], v[20:21] op_sel_hi:[1,0] neg_lo:[0,1] neg_hi:[0,1]
	v_pk_mul_f32 v[24:25], v[18:19], v[18:19]
	v_pk_mul_f32 v[26:27], v[22:23], v[22:23]
	v_add_f32_e32 v20, v24, v25
	v_add_f32_e32 v20, v27, v20
	v_add_f32_e32 v20, v26, v20
	v_lshl_add_u64 v[26:27], v[76:77], 0, s[16:17]
	s_nop 0
	v_add_f32_dpp v20, v20, v20 quad_perm:[1,0,3,2] row_mask:0xf bank_mask:0xf bound_ctrl:1
	s_nop 1
	v_add_f32_dpp v20, v20, v20 quad_perm:[2,3,0,1] row_mask:0xf bank_mask:0xf bound_ctrl:1
	s_nop 1
	v_add_f32_dpp v20, v20, v20 row_half_mirror row_mask:0xf bank_mask:0xf bound_ctrl:1
	s_nop 1
	v_add_f32_dpp v20, v20, v20 row_mirror row_mask:0xf bank_mask:0xf bound_ctrl:1
	v_fmamk_f32 v20, v20, 0x3c800000, v164
	v_cmp_gt_f32_e32 vcc, s82, v20
	v_mul_f32_e32 v24, 0x4b800000, v20
	s_nop 0
	v_cndmask_b32_e32 v20, v20, v24, vcc
	v_rsq_f32_e32 v20, v20
	s_nop 0
	v_mul_f32_e32 v24, 0x45800000, v20
	v_cndmask_b32_e32 v20, v20, v24, vcc
	v_mul_f32_e32 v18, v18, v20
	v_cvt_pk_bf16_f32 v18, v18, v18
	ds_write_b16 v54, v18 offset:65056
	v_mul_f32_e32 v18, v19, v20
	v_cvt_pk_bf16_f32 v18, v18, v18
	ds_write_b16 v54, v18 offset:65088
	v_mul_f32_e32 v18, v23, v20
	v_cvt_pk_bf16_f32 v18, v18, v18
	ds_write_b16 v54, v18 offset:65120
	v_mul_f32_e32 v18, v22, v20
	v_cvt_pk_bf16_f32 v18, v18, v18
	ds_write_b16 v54, v18 offset:65152
	v_mul_f32_e32 v18, v89, v125
	v_mul_f32_e32 v18, 0x3fb8aa3b, v18
	v_exp_f32_e32 v18, v18
	v_mov_b32_e32 v89, v1
	v_pk_fma_f32 v[20:21], v[18:19], v[48:49], v[44:45] op_sel_hi:[0,1,1]
	v_pk_fma_f32 v[18:19], v[18:19], v[40:41], v[36:37] op_sel_hi:[0,1,1]
	v_add_f32_e32 v22, 0, v18
	v_add_f32_e32 v22, v22, v19
	v_add_f32_e32 v22, v22, v21
	v_add_f32_e32 v22, v22, v20
	s_nop 1
	v_add_f32_dpp v22, v22, v22 quad_perm:[1,0,3,2] row_mask:0xf bank_mask:0xf bound_ctrl:1
	s_nop 1
	v_add_f32_dpp v22, v22, v22 quad_perm:[2,3,0,1] row_mask:0xf bank_mask:0xf bound_ctrl:1
	s_nop 1
	v_add_f32_dpp v22, v22, v22 row_half_mirror row_mask:0xf bank_mask:0xf bound_ctrl:1
	s_nop 1
	v_add_f32_dpp v22, v22, v22 row_mirror row_mask:0xf bank_mask:0xf bound_ctrl:1
	v_mul_f32_e32 v22, 0x3c800000, v22
	v_pk_add_f32 v[18:19], v[18:19], v[22:23] op_sel_hi:[1,0] neg_lo:[0,1] neg_hi:[0,1]
	v_pk_add_f32 v[20:21], v[20:21], v[22:23] op_sel_hi:[1,0] neg_lo:[0,1] neg_hi:[0,1]
	v_pk_mul_f32 v[24:25], v[18:19], v[18:19]
	v_pk_mul_f32 v[22:23], v[20:21], v[20:21]
	v_add_f32_e32 v24, v24, v25
	v_add_f32_e32 v23, v23, v24
	v_add_f32_e32 v22, v22, v23
	s_nop 1
	v_add_f32_dpp v22, v22, v22 quad_perm:[1,0,3,2] row_mask:0xf bank_mask:0xf bound_ctrl:1
	s_nop 1
	v_add_f32_dpp v22, v22, v22 quad_perm:[2,3,0,1] row_mask:0xf bank_mask:0xf bound_ctrl:1
	s_nop 1
	v_add_f32_dpp v22, v22, v22 row_half_mirror row_mask:0xf bank_mask:0xf bound_ctrl:1
	s_nop 1
	v_add_f32_dpp v22, v22, v22 row_mirror row_mask:0xf bank_mask:0xf bound_ctrl:1
	v_fmamk_f32 v22, v22, 0x3c800000, v164
	v_cmp_gt_f32_e32 vcc, s82, v22
	v_mul_f32_e32 v23, 0x4b800000, v22
	s_nop 0
	v_cndmask_b32_e32 v22, v22, v23, vcc
	v_rsq_f32_e32 v22, v22
	s_nop 0
	v_mul_f32_e32 v23, 0x45800000, v22
	v_cndmask_b32_e32 v22, v22, v23, vcc
	v_mul_f32_e32 v18, v18, v22
	v_cvt_pk_bf16_f32 v18, v18, v18
	ds_write_b16 v54, v18 offset:65328
	v_mul_f32_e32 v18, v19, v22
	v_cvt_pk_bf16_f32 v18, v18, v18
	ds_write_b16 v54, v18 offset:65360
	v_mul_f32_e32 v18, v21, v22
	v_cvt_pk_bf16_f32 v18, v18, v18
	ds_write_b16 v54, v18 offset:65392
	v_mul_f32_e32 v18, v20, v22
	v_mad_u64_u32 v[22:23], s[82:83], v30, s89, v[28:29]
	v_mov_b32_e32 v24, v23
	v_mad_u64_u32 v[24:25], s[82:83], v31, s89, v[24:25]
	v_mov_b32_e32 v23, v24
	v_lshl_add_u64 v[22:23], v[22:23], 0, s[16:17]
	v_lshl_add_u64 v[22:23], v[22:23], 0, v[88:89]
	v_cvt_pk_bf16_f32 v18, v18, v18
	ds_write_b16 v54, v18 offset:65424
	v_add_u32_e32 v18, v68, v126
	ds_read_b128 v[18:21], v18 offset:64512
	s_andn2_b64 vcc, exec, s[90:91]
	s_waitcnt lgkmcnt(0)
; __device__ __forceinline__ unsigned pk2(float lo, float hi) { unsigned r; asm("v_cvt_pk_bf16_f32 %0, %1, %2" : "=v"(r) : "v"(lo), "v"(hi)); return r; }
; __device__ __forceinline__ float sigmoidf_(float x) { return __builtin_amdgcn_rcpf(1.f + __builtin_amdgcn_exp2f(x * -1.4426950408889634f)); }
; __device__ __forceinline__ void ret_out_phase(const bf16* Z, const bf16* SP, bf16* MIX, unsigned char* lds) {
;     ...
;         for (int t2 = 0; t2 < 2; ++t2) { const int cidx = lane + 64 * t2, i = 16 * wave + (cidx >> 3), c8 = (cidx & 7) * 8;
;             const u32x4 ov = *(const u32x4*)(Ps + i * 136 + c8), gv = *(const u32x4*)(Z + (rowbase + i) * EVEN_IN + 1536 + h * 64 + c8); u32x4 w;
; #pragma unroll
;             for (int x = 0; x < 4; ++x) { const float g0 = __uint_as_float(gv[x] << 16), g1 = __uint_as_float(gv[x] & 0xffff0000u);
;                 w[x] = pk2(__uint_as_float(ov[x] << 16) * g0 * sigmoidf_(g0), __uint_as_float(ov[x] & 0xffff0000u) * g1 * sigmoidf_(g1)); }
;             *(u32x4*)(MIX + (rowbase + i) * DM + h * 64 + c8) = w; }
	v_lshlrev_b32_e32 v33, 16, v18
	v_and_b32_e32 v18, 0xffff0000, v18
	s_waitcnt vmcnt(1)
	v_mov_b64_e32 v[22:23], v[174:175]
	v_mov_b64_e32 v[24:25], v[176:177]
	v_lshlrev_b32_e32 v32, 16, v22
	v_and_b32_e32 v22, 0xffff0000, v22
	v_mul_f32_e32 v33, v32, v33
	v_mul_f32_e32 v32, 0xbfb8aa3b, v32
	v_mul_f32_e32 v18, v22, v18
	v_mul_f32_e32 v22, 0xbfb8aa3b, v22
	v_exp_f32_e32 v32, v32
	v_exp_f32_e32 v22, v22
	v_add_f32_e32 v32, 1.0, v32
	v_add_f32_e32 v22, 1.0, v22
	v_rcp_f32_e32 v32, v32
	v_rcp_f32_e32 v22, v22
	v_mul_f32_e32 v32, v33, v32
	v_mul_f32_e32 v18, v18, v22
	v_cvt_pk_bf16_f32 v18, v32, v18
	v_lshlrev_b32_e32 v22, 16, v23
	v_lshlrev_b32_e32 v32, 16, v19
	v_and_b32_e32 v23, 0xffff0000, v23
	v_and_b32_e32 v19, 0xffff0000, v19
	v_mul_f32_e32 v32, v22, v32
	v_mul_f32_e32 v22, 0xbfb8aa3b, v22
	v_mul_f32_e32 v19, v23, v19
	v_mul_f32_e32 v23, 0xbfb8aa3b, v23
	v_exp_f32_e32 v22, v22
	v_exp_f32_e32 v23, v23
	v_add_f32_e32 v22, 1.0, v22
	v_add_f32_e32 v23, 1.0, v23
	v_rcp_f32_e32 v22, v22
	v_rcp_f32_e32 v23, v23
	v_mul_f32_e32 v22, v32, v22
	v_mul_f32_e32 v19, v19, v23
	v_cvt_pk_bf16_f32 v19, v22, v19
	v_lshlrev_b32_e32 v22, 16, v24
	v_lshlrev_b32_e32 v23, 16, v20
	v_mul_f32_e32 v23, v22, v23
	v_mul_f32_e32 v22, 0xbfb8aa3b, v22
	v_exp_f32_e32 v22, v22
	v_and_b32_e32 v20, 0xffff0000, v20
	v_add_f32_e32 v22, 1.0, v22
	v_rcp_f32_e32 v22, v22
	s_nop 0
	v_mul_f32_e32 v22, v23, v22
	v_and_b32_e32 v23, 0xffff0000, v24
	v_mul_f32_e32 v20, v23, v20
	v_mul_f32_e32 v23, 0xbfb8aa3b, v23
	v_exp_f32_e32 v23, v23
	s_nop 0
	v_add_f32_e32 v23, 1.0, v23
	v_rcp_f32_e32 v23, v23
	s_nop 0
	v_mul_f32_e32 v20, v20, v23
	v_cvt_pk_bf16_f32 v20, v22, v20
	v_lshlrev_b32_e32 v22, 16, v25
	v_lshlrev_b32_e32 v23, 16, v21
	v_mul_f32_e32 v23, v22, v23
	v_mul_f32_e32 v22, 0xbfb8aa3b, v22
	v_exp_f32_e32 v22, v22
	v_and_b32_e32 v21, 0xffff0000, v21
	v_add_f32_e32 v22, 1.0, v22
	v_rcp_f32_e32 v22, v22
	s_nop 0
	v_mul_f32_e32 v22, v23, v22
	v_and_b32_e32 v23, 0xffff0000, v25
	v_mul_f32_e32 v21, v23, v21
	v_mul_f32_e32 v23, 0xbfb8aa3b, v23
	v_exp_f32_e32 v23, v23
	s_nop 0
	v_add_f32_e32 v23, 1.0, v23
	v_rcp_f32_e32 v23, v23
	s_nop 0
	v_mul_f32_e32 v21, v21, v23
	v_cvt_pk_bf16_f32 v21, v22, v21
	v_lshlrev_b64 v[22:23], 11, v[30:31]
	v_lshl_add_u64 v[22:23], v[26:27], 0, v[22:23]
	global_store_dwordx4 v[22:23], v[18:21], off
	ds_read_b128 v[20:23], v130 offset:64512
	s_nop 0
	v_lshl_add_u64 v[18:19], s[84:85], 0, v[86:87]
	v_mad_u64_u32 v[24:25], s[82:83], v18, s89, v[28:29]
	v_mov_b32_e32 v28, v25
	v_mad_u64_u32 v[28:29], s[82:83], v19, s89, v[28:29]
	v_mov_b32_e32 v25, v28
	v_lshl_add_u64 v[24:25], v[24:25], 0, s[16:17]
	v_lshl_add_u64 v[24:25], v[24:25], 0, v[88:89]
	s_waitcnt lgkmcnt(0)
	v_lshlrev_b32_e32 v25, 16, v20
	v_and_b32_e32 v20, 0xffff0000, v20
	v_lshlrev_b64 v[18:19], 11, v[18:19]
	v_readlane_b32 s82, v240, 40
	v_lshl_add_u64 v[18:19], v[26:27], 0, v[18:19]
	s_add_i32 s96, s96, s82
	s_waitcnt vmcnt(1)
	v_mov_b64_e32 v[28:29], v[184:185]
	v_mov_b64_e32 v[30:31], v[186:187]
	v_lshlrev_b32_e32 v24, 16, v28
	v_mul_f32_e32 v25, v24, v25
	v_mul_f32_e32 v24, 0xbfb8aa3b, v24
	v_exp_f32_e32 v24, v24
	s_nop 0
	v_add_f32_e32 v24, 1.0, v24
	v_rcp_f32_e32 v24, v24
	s_nop 0
	v_mul_f32_e32 v24, v25, v24
	v_and_b32_e32 v25, 0xffff0000, v28
	v_mul_f32_e32 v20, v25, v20
	v_mul_f32_e32 v25, 0xbfb8aa3b, v25
	v_exp_f32_e32 v25, v25
	s_nop 0
	v_add_f32_e32 v25, 1.0, v25
	v_rcp_f32_e32 v25, v25
	s_nop 0
	v_mul_f32_e32 v20, v20, v25
	v_cvt_pk_bf16_f32 v20, v24, v20
	v_lshlrev_b32_e32 v24, 16, v29
	v_lshlrev_b32_e32 v25, 16, v21
	v_mul_f32_e32 v25, v24, v25
	v_mul_f32_e32 v24, 0xbfb8aa3b, v24
	v_exp_f32_e32 v24, v24
	v_and_b32_e32 v21, 0xffff0000, v21
	v_add_f32_e32 v24, 1.0, v24
	v_rcp_f32_e32 v24, v24
	s_nop 0
	v_mul_f32_e32 v24, v25, v24
	v_and_b32_e32 v25, 0xffff0000, v29
	v_mul_f32_e32 v21, v25, v21
	v_mul_f32_e32 v25, 0xbfb8aa3b, v25
	v_exp_f32_e32 v25, v25
	s_nop 0
	v_add_f32_e32 v25, 1.0, v25
	v_rcp_f32_e32 v25, v25
	s_nop 0
	v_mul_f32_e32 v21, v21, v25
	v_cvt_pk_bf16_f32 v21, v24, v21
	v_lshlrev_b32_e32 v24, 16, v30
	v_lshlrev_b32_e32 v25, 16, v22
	v_mul_f32_e32 v25, v24, v25
	v_mul_f32_e32 v24, 0xbfb8aa3b, v24
	v_exp_f32_e32 v24, v24
	v_and_b32_e32 v22, 0xffff0000, v22
	v_add_f32_e32 v24, 1.0, v24
	v_rcp_f32_e32 v24, v24
	s_nop 0
	v_mul_f32_e32 v24, v25, v24
	v_and_b32_e32 v25, 0xffff0000, v30
	v_mul_f32_e32 v22, v25, v22
	v_mul_f32_e32 v25, 0xbfb8aa3b, v25
	v_exp_f32_e32 v25, v25
	s_nop 0
	v_add_f32_e32 v25, 1.0, v25
	v_rcp_f32_e32 v25, v25
	s_nop 0
	v_mul_f32_e32 v22, v22, v25
	v_cvt_pk_bf16_f32 v22, v24, v22
	v_lshlrev_b32_e32 v24, 16, v31
	v_lshlrev_b32_e32 v25, 16, v23
	v_mul_f32_e32 v25, v24, v25
	v_mul_f32_e32 v24, 0xbfb8aa3b, v24
	v_exp_f32_e32 v24, v24
	v_and_b32_e32 v23, 0xffff0000, v23
	v_add_f32_e32 v24, 1.0, v24
	v_rcp_f32_e32 v24, v24
	s_nop 0
	v_mul_f32_e32 v24, v25, v24
	v_and_b32_e32 v25, 0xffff0000, v31
	v_mul_f32_e32 v23, v25, v23
	v_mul_f32_e32 v25, 0xbfb8aa3b, v25
	v_exp_f32_e32 v25, v25
	s_nop 0
	v_add_f32_e32 v25, 1.0, v25
	v_rcp_f32_e32 v25, v25
	s_nop 0
	v_mul_f32_e32 v23, v23, v25
	v_cvt_pk_bf16_f32 v23, v24, v23
	global_store_dwordx4 v[18:19], v[20:23], off
	s_cbranch_vccz .LBB0_638
